# attention: sc1 nt (streaming) on the single-use Q-fragment loads and gate-z loads
# baseline (speedup 1.0000x reference)
.LBB0_1258:
	s_bfe_u32 s41, s0, 0x20004
	s_and_b32 s40, s0, 15
	s_lshl_b32 s0, s0, 2
	s_and_b32 s0, s0, 0xffffff00
	v_subrev_u32_e32 v2, s0, v215
	v_add_u32_e32 v206, 0xf00, v2
	v_or_b32_e32 v208, v206, v214
	s_lshl_b32 s8, s41, 12
	v_ashrrev_i32_e32 v209, 31, v208
	v_lshl_add_u64 v[4:5], s[8:9], 0, v[208:209]
	v_mov_b64_e32 v[6:7], s[6:7]
	v_mad_u64_u32 v[6:7], s[10:11], v4, s19, v[6:7]
	v_mad_i32_i24 v7, v5, s19, v7
	s_mul_i32 s8, s40, 0x180
	v_lshl_add_u64 v[4:5], v[6:7], 0, s[8:9]
	v_lshlrev_b32_e32 v0, 1, v180
	v_lshl_add_u64 v[4:5], v[4:5], 0, v[0:1]
	global_load_dwordx4 v[112:115], v[4:5], off sc1 nt
	global_load_dwordx4 v[116:119], v[4:5], off offset:32 sc1 nt
	global_load_dwordx4 v[120:123], v[4:5], off offset:64 sc1 nt
	global_load_dwordx4 v[124:127], v[4:5], off offset:96 sc1 nt
	global_load_dwordx4 v[128:131], v[4:5], off offset:128 sc1 nt
	global_load_dwordx4 v[132:135], v[4:5], off offset:160 sc1 nt
	global_load_dwordx4 v[136:139], v[4:5], off offset:192 sc1 nt
	global_load_dwordx4 v[140:143], v[4:5], off offset:224 sc1 nt
	global_load_dwordx4 v[144:147], v[4:5], off offset:256 sc1 nt
	global_load_dwordx4 v[148:151], v[4:5], off offset:288 sc1 nt
	global_load_dwordx4 v[152:155], v[4:5], off offset:320 sc1 nt
	global_load_dwordx4 v[156:159], v[4:5], off offset:352 sc1 nt
	s_lshl_b32 s8, s40, 15
	v_add_u32_e32 v0, s18, v216
	v_lshl_add_u64 v[4:5], v[184:185], 0, s[8:9]
	v_readfirstlane_b32 s1, v0
	v_add_u32_e32 v3, 0x2000, v0
	v_lshl_add_u64 v[6:7], v[182:183], 1, v[4:5]
	s_mov_b32 m0, s1
	v_readfirstlane_b32 s1, v3
	v_add_u32_e32 v3, 0x4000, v0
	global_load_lds_dwordx4 v[6:7], off
	v_lshl_add_u64 v[6:7], v[196:197], 1, v[4:5]
	s_mov_b32 m0, s1
	v_readfirstlane_b32 s1, v3
	v_add_u32_e32 v0, 0x6000, v0
	global_load_lds_dwordx4 v[6:7], off
	v_lshl_add_u64 v[6:7], v[198:199], 1, v[4:5]
	s_mov_b32 m0, s1
	v_readfirstlane_b32 s1, v0
	global_load_lds_dwordx4 v[6:7], off
	v_lshl_add_u64 v[4:5], v[200:201], 1, v[4:5]
	s_mov_b32 m0, s1
	s_cmpk_eq_i32 s0, 0x1000
	global_load_lds_dwordx4 v[4:5], off
	s_cbranch_scc1 .LBB0_1269
	s_sub_i32 s0, 0x1000, s0
	s_lshr_b32 s42, s0, 6
	s_mul_i32 s0, s41, 0x180000
	s_add_u32 s0, s3, s0
	s_addc_u32 s1, s14, 0
	s_lshl_b32 s8, s41, 20
	s_add_u32 s10, s15, s8
	s_addc_u32 s11, s16, 0
	v_lshl_add_u64 v[4:5], s[10:11], 0, v[192:193]
	v_lshl_add_u64 v[6:7], s[10:11], 0, v[194:195]
	v_mov_b32_e32 v205, v1
	v_lshl_add_u64 v[210:211], v[4:5], 0, v[204:205]
	v_lshl_add_u64 v[212:213], v[6:7], 0, v[204:205]
	global_load_dwordx4 v[164:167], v[212:213], off
	global_load_dwordx4 v[160:163], v[210:211], off
	global_load_dwordx4 v[176:179], v190, s[0:1]
	global_load_dwordx4 v[168:171], v188, s[0:1]
	global_load_dwordx4 v[172:175], v186, s[0:1]
	v_subrev_u32_e32 v210, s34, v210
	v_subrev_u32_e32 v212, s34, v212
	v_mov_b32_e32 v14, v1
	v_mov_b32_e32 v15, v1
	v_add_u32_e32 v207, 0xf1f, v2
	v_mov_b32_e32 v0, v1
	v_mov_b32_e32 v2, v1
	v_mov_b32_e32 v3, v1
	v_mov_b32_e32 v4, v1
	v_mov_b32_e32 v5, v1
	v_mov_b32_e32 v6, v1
	v_mov_b32_e32 v7, v1
	v_mov_b32_e32 v8, v1
	v_mov_b32_e32 v9, v1
	v_mov_b32_e32 v10, v1
	v_mov_b32_e32 v11, v1
	v_mov_b32_e32 v12, v1
	v_mov_b32_e32 v13, v1
	v_mov_b64_e32 v[78:79], v[14:15]
	v_mov_b64_e32 v[62:63], v[14:15]
	v_mov_b64_e32 v[46:47], v[14:15]
	v_mov_b64_e32 v[30:31], v[14:15]
	s_mov_b32 s43, 0
	v_mov_b32_e32 v209, 0xf149f2ca
	v_mov_b32_e32 v205, 0
	v_mov_b64_e32 v[76:77], v[12:13]
	v_mov_b64_e32 v[74:75], v[10:11]
	v_mov_b64_e32 v[72:73], v[8:9]
	v_mov_b64_e32 v[70:71], v[6:7]
	v_mov_b64_e32 v[68:69], v[4:5]
	v_mov_b64_e32 v[66:67], v[2:3]
	v_mov_b64_e32 v[64:65], v[0:1]
	v_mov_b64_e32 v[60:61], v[12:13]
	v_mov_b64_e32 v[58:59], v[10:11]
	v_mov_b64_e32 v[56:57], v[8:9]
	v_mov_b64_e32 v[54:55], v[6:7]
	v_mov_b64_e32 v[52:53], v[4:5]
	v_mov_b64_e32 v[50:51], v[2:3]
	v_mov_b64_e32 v[48:49], v[0:1]
	v_mov_b64_e32 v[44:45], v[12:13]
	v_mov_b64_e32 v[42:43], v[10:11]
	v_mov_b64_e32 v[40:41], v[8:9]
	v_mov_b64_e32 v[38:39], v[6:7]
	v_mov_b64_e32 v[36:37], v[4:5]
	v_mov_b64_e32 v[34:35], v[2:3]
	v_mov_b64_e32 v[32:33], v[0:1]
	v_mov_b64_e32 v[28:29], v[12:13]
	v_mov_b64_e32 v[26:27], v[10:11]
	v_mov_b64_e32 v[24:25], v[8:9]
	v_mov_b64_e32 v[22:23], v[6:7]
	v_mov_b64_e32 v[20:21], v[4:5]
	v_mov_b64_e32 v[18:19], v[2:3]
	v_mov_b64_e32 v[16:17], v[0:1]
	s_mov_b32 s44, 0
	s_waitcnt vmcnt(0) lgkmcnt(0)
	s_barrier
	ds_write_b128 v236, v[172:175]
	ds_write_b128 v237, v[168:171]
	ds_write_b128 v238, v[176:179]
	ds_write2_b64 v245, v[160:161], v[162:163] offset1:2
	ds_write2_b64 v246, v[164:165], v[166:167] offset1:2
	v_add_u32_e32 v236, 0x1a000, v236
	v_add_u32_e32 v237, 0x1a000, v237
	v_add_u32_e32 v238, 0x1a000, v238
	v_add_u32_e32 v245, 0x4800, v245
	v_add_u32_e32 v246, 0x4800, v246
	s_cmp_lt_u32 s42, 2
	s_cbranch_scc1 .Lattn_p1
	s_mov_b32 s8, 64
	s_mul_i32 s10, s8, 0x180
	s_mul_hi_u32 s11, s8, 0x180
	s_add_u32 s10, s0, s10
	s_addc_u32 s11, s1, s11
	global_load_dwordx4 v[172:175], v186, s[10:11]
	global_load_dwordx4 v[168:171], v188, s[10:11]
	global_load_dwordx4 v[176:179], v190, s[10:11]
	s_lshl_b32 s10, s8, 1
	s_add_u32 s10, s34, s10
	s_addc_u32 s11, s35, 0
	global_load_dwordx4 v[160:163], v210, s[10:11]
	global_load_dwordx4 v[164:167], v212, s[10:11]

.LBB0_1271:
	v_lshl_add_u64 v[28:29], v[2:3], 0, s[10:11]
	v_add_co_u32_e64 v38, s[0:1], s36, v28
	v_add_co_u32_e32 v36, vcc, 0xc000000, v28
	s_nop 0
	v_addc_co_u32_e64 v39, s[0:1], 0, v29, s[0:1]
	v_add_co_u32_e64 v40, s[0:1], s37, v28
	v_addc_co_u32_e32 v37, vcc, 0, v29, vcc
	s_nop 0
	v_addc_co_u32_e64 v41, s[0:1], 0, v29, s[0:1]
	v_add_co_u32_e64 v42, s[0:1], s38, v28
	ds_read_b128 v[4:7], v0
	ds_read_b128 v[8:11], v0 offset:1088
	ds_read_b128 v[12:15], v0 offset:2176
	ds_read_b128 v[16:19], v0 offset:3264
	v_addc_co_u32_e64 v43, s[0:1], 0, v29, s[0:1]
	global_load_dwordx4 v[20:23], v[40:41], off sc1 nt
	global_load_dwordx4 v[24:27], v[42:43], off sc1 nt
	global_load_dwordx4 v[28:31], v[36:37], off sc1 nt
	global_load_dwordx4 v[32:35], v[38:39], off sc1 nt
	s_add_u32 s10, s10, 0x10000
	s_waitcnt lgkmcnt(1)
	v_lshlrev_b32_e32 v52, 16, v12
	v_and_b32_e32 v53, 0xffff0000, v12
	v_lshlrev_b32_e32 v12, 16, v13
	v_and_b32_e32 v13, 0xffff0000, v13
	v_lshlrev_b32_e32 v54, 16, v14
	v_and_b32_e32 v55, 0xffff0000, v14
	v_lshlrev_b32_e32 v14, 16, v15
	v_and_b32_e32 v15, 0xffff0000, v15
	s_addc_u32 s11, s11, 0
	v_lshlrev_b32_e32 v44, 16, v4
	v_and_b32_e32 v45, 0xffff0000, v4
	v_lshlrev_b32_e32 v4, 16, v5
	v_and_b32_e32 v5, 0xffff0000, v5
	v_lshlrev_b32_e32 v46, 16, v6
	v_and_b32_e32 v47, 0xffff0000, v6
	v_lshlrev_b32_e32 v6, 16, v7
	v_and_b32_e32 v7, 0xffff0000, v7
	v_lshlrev_b32_e32 v48, 16, v8
	v_and_b32_e32 v49, 0xffff0000, v8
	v_lshlrev_b32_e32 v8, 16, v9
	v_and_b32_e32 v9, 0xffff0000, v9
	v_lshlrev_b32_e32 v50, 16, v10
	v_and_b32_e32 v51, 0xffff0000, v10
	v_lshlrev_b32_e32 v10, 16, v11
	v_and_b32_e32 v11, 0xffff0000, v11
	s_waitcnt lgkmcnt(0)
	v_lshlrev_b32_e32 v56, 16, v16
	v_and_b32_e32 v57, 0xffff0000, v16
	v_lshlrev_b32_e32 v16, 16, v17
	v_and_b32_e32 v17, 0xffff0000, v17
	v_lshlrev_b32_e32 v58, 16, v18
	v_and_b32_e32 v59, 0xffff0000, v18
	v_lshlrev_b32_e32 v18, 16, v19
	v_and_b32_e32 v19, 0xffff0000, v19
	v_add_u32_e32 v0, 0x1100, v0
	s_cmp_eq_u32 s10, 0x20000
	s_waitcnt vmcnt(3)
	v_lshlrev_b32_e32 v60, 16, v20
	v_and_b32_e32 v61, 0xffff0000, v20
	v_lshlrev_b32_e32 v20, 16, v21
	v_and_b32_e32 v21, 0xffff0000, v21
	v_lshlrev_b32_e32 v62, 16, v22
	v_and_b32_e32 v63, 0xffff0000, v22
	v_lshlrev_b32_e32 v22, 16, v23
	v_and_b32_e32 v23, 0xffff0000, v23
	s_waitcnt vmcnt(2)
	v_lshlrev_b32_e32 v64, 16, v24
	v_and_b32_e32 v65, 0xffff0000, v24
	v_lshlrev_b32_e32 v24, 16, v25
	v_and_b32_e32 v25, 0xffff0000, v25
	v_lshlrev_b32_e32 v66, 16, v26
	v_and_b32_e32 v67, 0xffff0000, v26
	v_lshlrev_b32_e32 v26, 16, v27
	v_and_b32_e32 v27, 0xffff0000, v27
	s_waitcnt vmcnt(1)
	v_lshlrev_b32_e32 v68, 16, v28
	v_and_b32_e32 v69, 0xffff0000, v28
	v_lshlrev_b32_e32 v28, 16, v29
	v_and_b32_e32 v29, 0xffff0000, v29
	v_lshlrev_b32_e32 v70, 16, v30
	v_and_b32_e32 v71, 0xffff0000, v30
	v_lshlrev_b32_e32 v30, 16, v31
	v_and_b32_e32 v31, 0xffff0000, v31
	s_waitcnt vmcnt(0)
	v_lshlrev_b32_e32 v72, 16, v32
	v_and_b32_e32 v73, 0xffff0000, v32
	v_lshlrev_b32_e32 v32, 16, v33
	v_and_b32_e32 v33, 0xffff0000, v33
	v_lshlrev_b32_e32 v74, 16, v34
	v_and_b32_e32 v75, 0xffff0000, v34
	v_lshlrev_b32_e32 v34, 16, v35
	v_and_b32_e32 v35, 0xffff0000, v35
	v_pk_mul_f32 v[52:53], v[52:53], v[60:61]
	v_pk_mul_f32 v[12:13], v[12:13], v[20:21]
	v_pk_mul_f32 v[20:21], v[54:55], v[62:63]
	v_pk_mul_f32 v[14:15], v[14:15], v[22:23]
	v_pk_mul_f32 v[22:23], v[56:57], v[64:65]
	v_pk_mul_f32 v[16:17], v[16:17], v[24:25]
	v_pk_mul_f32 v[24:25], v[58:59], v[66:67]
	v_pk_mul_f32 v[18:19], v[18:19], v[26:27]
	v_pk_mul_f32 v[26:27], v[44:45], v[68:69]
	v_pk_mul_f32 v[28:29], v[4:5], v[28:29]
	v_pk_mul_f32 v[44:45], v[46:47], v[70:71]
	v_pk_mul_f32 v[30:31], v[6:7], v[30:31]
	v_pk_mul_f32 v[46:47], v[48:49], v[72:73]
	v_pk_mul_f32 v[32:33], v[8:9], v[32:33]
	v_pk_mul_f32 v[48:49], v[50:51], v[74:75]
	v_pk_mul_f32 v[34:35], v[10:11], v[34:35]
	v_cvt_pk_bf16_f32 v4, v52, v53
	v_cvt_pk_bf16_f32 v5, v12, v13
	v_cvt_pk_bf16_f32 v6, v20, v21
	v_cvt_pk_bf16_f32 v7, v14, v15
	v_cvt_pk_bf16_f32 v8, v22, v23
	v_cvt_pk_bf16_f32 v9, v16, v17
	v_cvt_pk_bf16_f32 v10, v24, v25
	v_cvt_pk_bf16_f32 v11, v18, v19
	v_cvt_pk_bf16_f32 v12, v26, v27
	v_cvt_pk_bf16_f32 v13, v28, v29
	v_cvt_pk_bf16_f32 v14, v44, v45
	v_cvt_pk_bf16_f32 v15, v30, v31
	v_cvt_pk_bf16_f32 v16, v46, v47
	v_cvt_pk_bf16_f32 v17, v32, v33
	v_cvt_pk_bf16_f32 v18, v48, v49
	v_cvt_pk_bf16_f32 v19, v34, v35
	global_store_dwordx4 v[40:41], v[4:7], off sc1
	global_store_dwordx4 v[42:43], v[8:11], off sc1
	global_store_dwordx4 v[36:37], v[12:15], off sc1
	global_store_dwordx4 v[38:39], v[16:19], off sc1
	s_cbranch_scc0 .LBB0_1271
	s_add_i32 s1, s39, 1
	s_bitcmp0_b32 s39, 0
	s_cselect_b32 s0, s17, s2
	s_mul_i32 s8, s1, s82
	s_add_i32 s0, s0, s8
	s_cmpk_gt_i32 s0, 0x3ff
	s_mov_b32 s39, s1
	s_barrier
	s_cbranch_scc0 .LBB0_1258
